# phase0 mod_partials: 64 loads in flight + v_readlane broadcasts instead of ds_bpermute
# speedup vs baseline: 1.0191x; 1.0191x over previous
.LBB0_21:
	global_load_dword v132, v[12:13], off nt
	v_add_co_u32_e32 v12, vcc, 0x3000, v12
	s_nop 1
	v_addc_co_u32_e32 v13, vcc, 0, v13, vcc
	global_load_dword v133, v[12:13], off nt
	v_add_co_u32_e32 v12, vcc, 0x3000, v12
	s_nop 1
	v_addc_co_u32_e32 v13, vcc, 0, v13, vcc
	global_load_dword v134, v[12:13], off nt
	v_add_co_u32_e32 v12, vcc, 0x3000, v12
	s_nop 1
	v_addc_co_u32_e32 v13, vcc, 0, v13, vcc
	global_load_dword v135, v[12:13], off nt
	v_add_co_u32_e32 v12, vcc, 0x3000, v12
	s_nop 1
	v_addc_co_u32_e32 v13, vcc, 0, v13, vcc
	global_load_dword v136, v[12:13], off nt
	v_add_co_u32_e32 v12, vcc, 0x3000, v12
	s_nop 1
	v_addc_co_u32_e32 v13, vcc, 0, v13, vcc
	global_load_dword v137, v[12:13], off nt
	v_add_co_u32_e32 v12, vcc, 0x3000, v12
	s_nop 1
	v_addc_co_u32_e32 v13, vcc, 0, v13, vcc
	global_load_dword v138, v[12:13], off nt
	v_add_co_u32_e32 v12, vcc, 0x3000, v12
	s_nop 1
	v_addc_co_u32_e32 v13, vcc, 0, v13, vcc
	global_load_dword v139, v[12:13], off nt
	v_add_co_u32_e32 v12, vcc, 0x3000, v12
	s_nop 1
	v_addc_co_u32_e32 v13, vcc, 0, v13, vcc
	global_load_dword v140, v[12:13], off nt
	v_add_co_u32_e32 v12, vcc, 0x3000, v12
	s_nop 1
	v_addc_co_u32_e32 v13, vcc, 0, v13, vcc
	global_load_dword v141, v[12:13], off nt
	v_add_co_u32_e32 v12, vcc, 0x3000, v12
	s_nop 1
	v_addc_co_u32_e32 v13, vcc, 0, v13, vcc
	global_load_dword v142, v[12:13], off nt
	v_add_co_u32_e32 v12, vcc, 0x3000, v12
	s_nop 1
	v_addc_co_u32_e32 v13, vcc, 0, v13, vcc
	global_load_dword v143, v[12:13], off nt
	v_add_co_u32_e32 v12, vcc, 0x3000, v12
	s_nop 1
	v_addc_co_u32_e32 v13, vcc, 0, v13, vcc
	global_load_dword v144, v[12:13], off nt
	v_add_co_u32_e32 v12, vcc, 0x3000, v12
	s_nop 1
	v_addc_co_u32_e32 v13, vcc, 0, v13, vcc
	global_load_dword v145, v[12:13], off nt
	v_add_co_u32_e32 v12, vcc, 0x3000, v12
	s_nop 1
	v_addc_co_u32_e32 v13, vcc, 0, v13, vcc
	global_load_dword v146, v[12:13], off nt
	v_add_co_u32_e32 v12, vcc, 0x3000, v12
	s_nop 1
	v_addc_co_u32_e32 v13, vcc, 0, v13, vcc
	global_load_dword v147, v[12:13], off nt
	v_add_co_u32_e32 v12, vcc, 0x3000, v12
	s_nop 1
	v_addc_co_u32_e32 v13, vcc, 0, v13, vcc
	global_load_dword v148, v[12:13], off nt
	v_add_co_u32_e32 v12, vcc, 0x3000, v12
	s_nop 1
	v_addc_co_u32_e32 v13, vcc, 0, v13, vcc
	global_load_dword v149, v[12:13], off nt
	v_add_co_u32_e32 v12, vcc, 0x3000, v12
	s_nop 1
	v_addc_co_u32_e32 v13, vcc, 0, v13, vcc
	global_load_dword v150, v[12:13], off nt
	v_add_co_u32_e32 v12, vcc, 0x3000, v12
	s_nop 1
	v_addc_co_u32_e32 v13, vcc, 0, v13, vcc
	global_load_dword v151, v[12:13], off nt
	v_add_co_u32_e32 v12, vcc, 0x3000, v12
	s_nop 1
	v_addc_co_u32_e32 v13, vcc, 0, v13, vcc
	global_load_dword v152, v[12:13], off nt
	v_add_co_u32_e32 v12, vcc, 0x3000, v12
	s_nop 1
	v_addc_co_u32_e32 v13, vcc, 0, v13, vcc
	global_load_dword v153, v[12:13], off nt
	v_add_co_u32_e32 v12, vcc, 0x3000, v12
	s_nop 1
	v_addc_co_u32_e32 v13, vcc, 0, v13, vcc
	global_load_dword v154, v[12:13], off nt
	v_add_co_u32_e32 v12, vcc, 0x3000, v12
	s_nop 1
	v_addc_co_u32_e32 v13, vcc, 0, v13, vcc
	global_load_dword v155, v[12:13], off nt
	v_add_co_u32_e32 v12, vcc, 0x3000, v12
	s_nop 1
	v_addc_co_u32_e32 v13, vcc, 0, v13, vcc
	global_load_dword v156, v[12:13], off nt
	v_add_co_u32_e32 v12, vcc, 0x3000, v12
	s_nop 1
	v_addc_co_u32_e32 v13, vcc, 0, v13, vcc
	global_load_dword v157, v[12:13], off nt
	v_add_co_u32_e32 v12, vcc, 0x3000, v12
	s_nop 1
	v_addc_co_u32_e32 v13, vcc, 0, v13, vcc
	global_load_dword v158, v[12:13], off nt
	v_add_co_u32_e32 v12, vcc, 0x3000, v12
	s_nop 1
	v_addc_co_u32_e32 v13, vcc, 0, v13, vcc
	global_load_dword v159, v[12:13], off nt
	v_add_co_u32_e32 v12, vcc, 0x3000, v12
	s_nop 1
	v_addc_co_u32_e32 v13, vcc, 0, v13, vcc
	global_load_dword v160, v[12:13], off nt
	v_add_co_u32_e32 v12, vcc, 0x3000, v12
	s_nop 1
	v_addc_co_u32_e32 v13, vcc, 0, v13, vcc
	global_load_dword v161, v[12:13], off nt
	v_add_co_u32_e32 v12, vcc, 0x3000, v12
	s_nop 1
	v_addc_co_u32_e32 v13, vcc, 0, v13, vcc
	global_load_dword v162, v[12:13], off nt
	v_add_co_u32_e32 v12, vcc, 0x3000, v12
	s_nop 1
	v_addc_co_u32_e32 v13, vcc, 0, v13, vcc
	global_load_dword v163, v[12:13], off nt
	v_add_co_u32_e32 v12, vcc, 0x3000, v12
	s_nop 1
	v_addc_co_u32_e32 v13, vcc, 0, v13, vcc
	global_load_dword v164, v[12:13], off nt
	v_add_co_u32_e32 v12, vcc, 0x3000, v12
	s_nop 1
	v_addc_co_u32_e32 v13, vcc, 0, v13, vcc
	global_load_dword v165, v[12:13], off nt
	v_add_co_u32_e32 v12, vcc, 0x3000, v12
	s_nop 1
	v_addc_co_u32_e32 v13, vcc, 0, v13, vcc
	global_load_dword v166, v[12:13], off nt
	v_add_co_u32_e32 v12, vcc, 0x3000, v12
	s_nop 1
	v_addc_co_u32_e32 v13, vcc, 0, v13, vcc
	global_load_dword v167, v[12:13], off nt
	v_add_co_u32_e32 v12, vcc, 0x3000, v12
	s_nop 1
	v_addc_co_u32_e32 v13, vcc, 0, v13, vcc
	global_load_dword v168, v[12:13], off nt
	v_add_co_u32_e32 v12, vcc, 0x3000, v12
	s_nop 1
	v_addc_co_u32_e32 v13, vcc, 0, v13, vcc
	global_load_dword v169, v[12:13], off nt
	v_add_co_u32_e32 v12, vcc, 0x3000, v12
	s_nop 1
	v_addc_co_u32_e32 v13, vcc, 0, v13, vcc
	global_load_dword v170, v[12:13], off nt
	v_add_co_u32_e32 v12, vcc, 0x3000, v12
	s_nop 1
	v_addc_co_u32_e32 v13, vcc, 0, v13, vcc
	global_load_dword v171, v[12:13], off nt
	v_add_co_u32_e32 v12, vcc, 0x3000, v12
	s_nop 1
	v_addc_co_u32_e32 v13, vcc, 0, v13, vcc
	global_load_dword v172, v[12:13], off nt
	v_add_co_u32_e32 v12, vcc, 0x3000, v12
	s_nop 1
	v_addc_co_u32_e32 v13, vcc, 0, v13, vcc
	global_load_dword v173, v[12:13], off nt
	v_add_co_u32_e32 v12, vcc, 0x3000, v12
	s_nop 1
	v_addc_co_u32_e32 v13, vcc, 0, v13, vcc
	global_load_dword v174, v[12:13], off nt
	v_add_co_u32_e32 v12, vcc, 0x3000, v12
	s_nop 1
	v_addc_co_u32_e32 v13, vcc, 0, v13, vcc
	global_load_dword v175, v[12:13], off nt
	v_add_co_u32_e32 v12, vcc, 0x3000, v12
	s_nop 1
	v_addc_co_u32_e32 v13, vcc, 0, v13, vcc
	global_load_dword v176, v[12:13], off nt
	v_add_co_u32_e32 v12, vcc, 0x3000, v12
	s_nop 1
	v_addc_co_u32_e32 v13, vcc, 0, v13, vcc
	global_load_dword v177, v[12:13], off nt
	v_add_co_u32_e32 v12, vcc, 0x3000, v12
	s_nop 1
	v_addc_co_u32_e32 v13, vcc, 0, v13, vcc
	global_load_dword v178, v[12:13], off nt
	v_add_co_u32_e32 v12, vcc, 0x3000, v12
	s_nop 1
	v_addc_co_u32_e32 v13, vcc, 0, v13, vcc
	global_load_dword v179, v[12:13], off nt
	v_add_co_u32_e32 v12, vcc, 0x3000, v12
	s_nop 1
	v_addc_co_u32_e32 v13, vcc, 0, v13, vcc
	global_load_dword v180, v[12:13], off nt
	v_add_co_u32_e32 v12, vcc, 0x3000, v12
	s_nop 1
	v_addc_co_u32_e32 v13, vcc, 0, v13, vcc
	global_load_dword v181, v[12:13], off nt
	v_add_co_u32_e32 v12, vcc, 0x3000, v12
	s_nop 1
	v_addc_co_u32_e32 v13, vcc, 0, v13, vcc
	global_load_dword v182, v[12:13], off nt
	v_add_co_u32_e32 v12, vcc, 0x3000, v12
	s_nop 1
	v_addc_co_u32_e32 v13, vcc, 0, v13, vcc
	global_load_dword v183, v[12:13], off nt
	v_add_co_u32_e32 v12, vcc, 0x3000, v12
	s_nop 1
	v_addc_co_u32_e32 v13, vcc, 0, v13, vcc
	global_load_dword v184, v[12:13], off nt
	v_add_co_u32_e32 v12, vcc, 0x3000, v12
	s_nop 1
	v_addc_co_u32_e32 v13, vcc, 0, v13, vcc
	global_load_dword v185, v[12:13], off nt
	v_add_co_u32_e32 v12, vcc, 0x3000, v12
	s_nop 1
	v_addc_co_u32_e32 v13, vcc, 0, v13, vcc
	global_load_dword v186, v[12:13], off nt
	v_add_co_u32_e32 v12, vcc, 0x3000, v12
	s_nop 1
	v_addc_co_u32_e32 v13, vcc, 0, v13, vcc
	global_load_dword v187, v[12:13], off nt
	v_add_co_u32_e32 v12, vcc, 0x3000, v12
	s_nop 1
	v_addc_co_u32_e32 v13, vcc, 0, v13, vcc
	global_load_dword v188, v[12:13], off nt
	v_add_co_u32_e32 v12, vcc, 0x3000, v12
	s_nop 1
	v_addc_co_u32_e32 v13, vcc, 0, v13, vcc
	global_load_dword v189, v[12:13], off nt
	v_add_co_u32_e32 v12, vcc, 0x3000, v12
	s_nop 1
	v_addc_co_u32_e32 v13, vcc, 0, v13, vcc
	global_load_dword v190, v[12:13], off nt
	v_add_co_u32_e32 v12, vcc, 0x3000, v12
	s_nop 1
	v_addc_co_u32_e32 v13, vcc, 0, v13, vcc
	global_load_dword v191, v[12:13], off nt
	v_add_co_u32_e32 v12, vcc, 0x3000, v12
	s_nop 1
	v_addc_co_u32_e32 v13, vcc, 0, v13, vcc
	global_load_dword v192, v[12:13], off nt
	v_add_co_u32_e32 v12, vcc, 0x3000, v12
	s_nop 1
	v_addc_co_u32_e32 v13, vcc, 0, v13, vcc
	global_load_dword v193, v[12:13], off nt
	v_add_co_u32_e32 v12, vcc, 0x3000, v12
	s_nop 1
	v_addc_co_u32_e32 v13, vcc, 0, v13, vcc
	global_load_dword v194, v[12:13], off nt
	v_add_co_u32_e32 v12, vcc, 0x3000, v12
	s_nop 1
	v_addc_co_u32_e32 v13, vcc, 0, v13, vcc
	global_load_dword v195, v[12:13], off nt
	v_readlane_b32 s12, v0, 0
	v_readlane_b32 s13, v23, 0
	v_readlane_b32 s14, v24, 0
	v_readlane_b32 s15, v25, 0
	v_readlane_b32 s16, v26, 0
	s_waitcnt vmcnt(63)
	v_pk_fma_f32 v[10:11], v[132:133], s[12:13], v[10:11] op_sel_hi:[0,1,1]
	v_pk_fma_f32 v[8:9], v[132:133], s[14:15], v[8:9] op_sel_hi:[0,1,1]
	v_fmac_f32_e32 v22, s16, v132
	v_readlane_b32 s12, v0, 1
	v_readlane_b32 s13, v23, 1
	v_readlane_b32 s14, v24, 1
	v_readlane_b32 s15, v25, 1
	v_readlane_b32 s16, v26, 1
	s_waitcnt vmcnt(62)
	v_pk_fma_f32 v[10:11], v[132:133], s[12:13], v[10:11] op_sel:[1,0,0] op_sel_hi:[1,1,1]
	v_pk_fma_f32 v[8:9], v[132:133], s[14:15], v[8:9] op_sel:[1,0,0] op_sel_hi:[1,1,1]
	v_fmac_f32_e32 v22, s16, v133
	v_readlane_b32 s12, v0, 2
	v_readlane_b32 s13, v23, 2
	v_readlane_b32 s14, v24, 2
	v_readlane_b32 s15, v25, 2
	v_readlane_b32 s16, v26, 2
	s_waitcnt vmcnt(61)
	v_pk_fma_f32 v[10:11], v[134:135], s[12:13], v[10:11] op_sel_hi:[0,1,1]
	v_pk_fma_f32 v[8:9], v[134:135], s[14:15], v[8:9] op_sel_hi:[0,1,1]
	v_fmac_f32_e32 v22, s16, v134
	v_readlane_b32 s12, v0, 3
	v_readlane_b32 s13, v23, 3
	v_readlane_b32 s14, v24, 3
	v_readlane_b32 s15, v25, 3
	v_readlane_b32 s16, v26, 3
	s_waitcnt vmcnt(60)
	v_pk_fma_f32 v[10:11], v[134:135], s[12:13], v[10:11] op_sel:[1,0,0] op_sel_hi:[1,1,1]
	v_pk_fma_f32 v[8:9], v[134:135], s[14:15], v[8:9] op_sel:[1,0,0] op_sel_hi:[1,1,1]
	v_fmac_f32_e32 v22, s16, v135
	v_readlane_b32 s12, v0, 4
	v_readlane_b32 s13, v23, 4
	v_readlane_b32 s14, v24, 4
	v_readlane_b32 s15, v25, 4
	v_readlane_b32 s16, v26, 4
	s_waitcnt vmcnt(59)
	v_pk_fma_f32 v[10:11], v[136:137], s[12:13], v[10:11] op_sel_hi:[0,1,1]
	v_pk_fma_f32 v[8:9], v[136:137], s[14:15], v[8:9] op_sel_hi:[0,1,1]
	v_fmac_f32_e32 v22, s16, v136
	v_readlane_b32 s12, v0, 5
	v_readlane_b32 s13, v23, 5
	v_readlane_b32 s14, v24, 5
	v_readlane_b32 s15, v25, 5
	v_readlane_b32 s16, v26, 5
	s_waitcnt vmcnt(58)
	v_pk_fma_f32 v[10:11], v[136:137], s[12:13], v[10:11] op_sel:[1,0,0] op_sel_hi:[1,1,1]
	v_pk_fma_f32 v[8:9], v[136:137], s[14:15], v[8:9] op_sel:[1,0,0] op_sel_hi:[1,1,1]
	v_fmac_f32_e32 v22, s16, v137
	v_readlane_b32 s12, v0, 6
	v_readlane_b32 s13, v23, 6
	v_readlane_b32 s14, v24, 6
	v_readlane_b32 s15, v25, 6
	v_readlane_b32 s16, v26, 6
	s_waitcnt vmcnt(57)
	v_pk_fma_f32 v[10:11], v[138:139], s[12:13], v[10:11] op_sel_hi:[0,1,1]
	v_pk_fma_f32 v[8:9], v[138:139], s[14:15], v[8:9] op_sel_hi:[0,1,1]
	v_fmac_f32_e32 v22, s16, v138
	v_readlane_b32 s12, v0, 7
	v_readlane_b32 s13, v23, 7
	v_readlane_b32 s14, v24, 7
	v_readlane_b32 s15, v25, 7
	v_readlane_b32 s16, v26, 7
	s_waitcnt vmcnt(56)
	v_pk_fma_f32 v[10:11], v[138:139], s[12:13], v[10:11] op_sel:[1,0,0] op_sel_hi:[1,1,1]
	v_pk_fma_f32 v[8:9], v[138:139], s[14:15], v[8:9] op_sel:[1,0,0] op_sel_hi:[1,1,1]
	v_fmac_f32_e32 v22, s16, v139
	v_readlane_b32 s12, v0, 8
	v_readlane_b32 s13, v23, 8
	v_readlane_b32 s14, v24, 8
	v_readlane_b32 s15, v25, 8
	v_readlane_b32 s16, v26, 8
	s_waitcnt vmcnt(55)
	v_pk_fma_f32 v[10:11], v[140:141], s[12:13], v[10:11] op_sel_hi:[0,1,1]
	v_pk_fma_f32 v[8:9], v[140:141], s[14:15], v[8:9] op_sel_hi:[0,1,1]
	v_fmac_f32_e32 v22, s16, v140
	v_readlane_b32 s12, v0, 9
	v_readlane_b32 s13, v23, 9
	v_readlane_b32 s14, v24, 9
	v_readlane_b32 s15, v25, 9
	v_readlane_b32 s16, v26, 9
	s_waitcnt vmcnt(54)
	v_pk_fma_f32 v[10:11], v[140:141], s[12:13], v[10:11] op_sel:[1,0,0] op_sel_hi:[1,1,1]
	v_pk_fma_f32 v[8:9], v[140:141], s[14:15], v[8:9] op_sel:[1,0,0] op_sel_hi:[1,1,1]
	v_fmac_f32_e32 v22, s16, v141
	v_readlane_b32 s12, v0, 10
	v_readlane_b32 s13, v23, 10
	v_readlane_b32 s14, v24, 10
	v_readlane_b32 s15, v25, 10
	v_readlane_b32 s16, v26, 10
	s_waitcnt vmcnt(53)
	v_pk_fma_f32 v[10:11], v[142:143], s[12:13], v[10:11] op_sel_hi:[0,1,1]
	v_pk_fma_f32 v[8:9], v[142:143], s[14:15], v[8:9] op_sel_hi:[0,1,1]
	v_fmac_f32_e32 v22, s16, v142
	v_readlane_b32 s12, v0, 11
	v_readlane_b32 s13, v23, 11
	v_readlane_b32 s14, v24, 11
	v_readlane_b32 s15, v25, 11
	v_readlane_b32 s16, v26, 11
	s_waitcnt vmcnt(52)
	v_pk_fma_f32 v[10:11], v[142:143], s[12:13], v[10:11] op_sel:[1,0,0] op_sel_hi:[1,1,1]
	v_pk_fma_f32 v[8:9], v[142:143], s[14:15], v[8:9] op_sel:[1,0,0] op_sel_hi:[1,1,1]
	v_fmac_f32_e32 v22, s16, v143
	v_readlane_b32 s12, v0, 12
	v_readlane_b32 s13, v23, 12
	v_readlane_b32 s14, v24, 12
	v_readlane_b32 s15, v25, 12
	v_readlane_b32 s16, v26, 12
	s_waitcnt vmcnt(51)
	v_pk_fma_f32 v[10:11], v[144:145], s[12:13], v[10:11] op_sel_hi:[0,1,1]
	v_pk_fma_f32 v[8:9], v[144:145], s[14:15], v[8:9] op_sel_hi:[0,1,1]
	v_fmac_f32_e32 v22, s16, v144
	v_readlane_b32 s12, v0, 13
	v_readlane_b32 s13, v23, 13
	v_readlane_b32 s14, v24, 13
	v_readlane_b32 s15, v25, 13
	v_readlane_b32 s16, v26, 13
	s_waitcnt vmcnt(50)
	v_pk_fma_f32 v[10:11], v[144:145], s[12:13], v[10:11] op_sel:[1,0,0] op_sel_hi:[1,1,1]
	v_pk_fma_f32 v[8:9], v[144:145], s[14:15], v[8:9] op_sel:[1,0,0] op_sel_hi:[1,1,1]
	v_fmac_f32_e32 v22, s16, v145
	v_readlane_b32 s12, v0, 14
	v_readlane_b32 s13, v23, 14
	v_readlane_b32 s14, v24, 14
	v_readlane_b32 s15, v25, 14
	v_readlane_b32 s16, v26, 14
	s_waitcnt vmcnt(49)
	v_pk_fma_f32 v[10:11], v[146:147], s[12:13], v[10:11] op_sel_hi:[0,1,1]
	v_pk_fma_f32 v[8:9], v[146:147], s[14:15], v[8:9] op_sel_hi:[0,1,1]
	v_fmac_f32_e32 v22, s16, v146
	v_readlane_b32 s12, v0, 15
	v_readlane_b32 s13, v23, 15
	v_readlane_b32 s14, v24, 15
	v_readlane_b32 s15, v25, 15
	v_readlane_b32 s16, v26, 15
	s_waitcnt vmcnt(48)
	v_pk_fma_f32 v[10:11], v[146:147], s[12:13], v[10:11] op_sel:[1,0,0] op_sel_hi:[1,1,1]
	v_pk_fma_f32 v[8:9], v[146:147], s[14:15], v[8:9] op_sel:[1,0,0] op_sel_hi:[1,1,1]
	v_fmac_f32_e32 v22, s16, v147
	v_readlane_b32 s12, v0, 16
	v_readlane_b32 s13, v23, 16
	v_readlane_b32 s14, v24, 16
	v_readlane_b32 s15, v25, 16
	v_readlane_b32 s16, v26, 16
	s_waitcnt vmcnt(47)
	v_pk_fma_f32 v[10:11], v[148:149], s[12:13], v[10:11] op_sel_hi:[0,1,1]
	v_pk_fma_f32 v[8:9], v[148:149], s[14:15], v[8:9] op_sel_hi:[0,1,1]
	v_fmac_f32_e32 v22, s16, v148
	v_readlane_b32 s12, v0, 17
	v_readlane_b32 s13, v23, 17
	v_readlane_b32 s14, v24, 17
	v_readlane_b32 s15, v25, 17
	v_readlane_b32 s16, v26, 17
	s_waitcnt vmcnt(46)
	v_pk_fma_f32 v[10:11], v[148:149], s[12:13], v[10:11] op_sel:[1,0,0] op_sel_hi:[1,1,1]
	v_pk_fma_f32 v[8:9], v[148:149], s[14:15], v[8:9] op_sel:[1,0,0] op_sel_hi:[1,1,1]
	v_fmac_f32_e32 v22, s16, v149
	v_readlane_b32 s12, v0, 18
	v_readlane_b32 s13, v23, 18
	v_readlane_b32 s14, v24, 18
	v_readlane_b32 s15, v25, 18
	v_readlane_b32 s16, v26, 18
	s_waitcnt vmcnt(45)
	v_pk_fma_f32 v[10:11], v[150:151], s[12:13], v[10:11] op_sel_hi:[0,1,1]
	v_pk_fma_f32 v[8:9], v[150:151], s[14:15], v[8:9] op_sel_hi:[0,1,1]
	v_fmac_f32_e32 v22, s16, v150
	v_readlane_b32 s12, v0, 19
	v_readlane_b32 s13, v23, 19
	v_readlane_b32 s14, v24, 19
	v_readlane_b32 s15, v25, 19
	v_readlane_b32 s16, v26, 19
	s_waitcnt vmcnt(44)
	v_pk_fma_f32 v[10:11], v[150:151], s[12:13], v[10:11] op_sel:[1,0,0] op_sel_hi:[1,1,1]
	v_pk_fma_f32 v[8:9], v[150:151], s[14:15], v[8:9] op_sel:[1,0,0] op_sel_hi:[1,1,1]
	v_fmac_f32_e32 v22, s16, v151
	v_readlane_b32 s12, v0, 20
	v_readlane_b32 s13, v23, 20
	v_readlane_b32 s14, v24, 20
	v_readlane_b32 s15, v25, 20
	v_readlane_b32 s16, v26, 20
	s_waitcnt vmcnt(43)
	v_pk_fma_f32 v[10:11], v[152:153], s[12:13], v[10:11] op_sel_hi:[0,1,1]
	v_pk_fma_f32 v[8:9], v[152:153], s[14:15], v[8:9] op_sel_hi:[0,1,1]
	v_fmac_f32_e32 v22, s16, v152
	v_readlane_b32 s12, v0, 21
	v_readlane_b32 s13, v23, 21
	v_readlane_b32 s14, v24, 21
	v_readlane_b32 s15, v25, 21
	v_readlane_b32 s16, v26, 21
	s_waitcnt vmcnt(42)
	v_pk_fma_f32 v[10:11], v[152:153], s[12:13], v[10:11] op_sel:[1,0,0] op_sel_hi:[1,1,1]
	v_pk_fma_f32 v[8:9], v[152:153], s[14:15], v[8:9] op_sel:[1,0,0] op_sel_hi:[1,1,1]
	v_fmac_f32_e32 v22, s16, v153
	v_readlane_b32 s12, v0, 22
	v_readlane_b32 s13, v23, 22
	v_readlane_b32 s14, v24, 22
	v_readlane_b32 s15, v25, 22
	v_readlane_b32 s16, v26, 22
	s_waitcnt vmcnt(41)
	v_pk_fma_f32 v[10:11], v[154:155], s[12:13], v[10:11] op_sel_hi:[0,1,1]
	v_pk_fma_f32 v[8:9], v[154:155], s[14:15], v[8:9] op_sel_hi:[0,1,1]
	v_fmac_f32_e32 v22, s16, v154
	v_readlane_b32 s12, v0, 23
	v_readlane_b32 s13, v23, 23
	v_readlane_b32 s14, v24, 23
	v_readlane_b32 s15, v25, 23
	v_readlane_b32 s16, v26, 23
	s_waitcnt vmcnt(40)
	v_pk_fma_f32 v[10:11], v[154:155], s[12:13], v[10:11] op_sel:[1,0,0] op_sel_hi:[1,1,1]
	v_pk_fma_f32 v[8:9], v[154:155], s[14:15], v[8:9] op_sel:[1,0,0] op_sel_hi:[1,1,1]
	v_fmac_f32_e32 v22, s16, v155
	v_readlane_b32 s12, v0, 24
	v_readlane_b32 s13, v23, 24
	v_readlane_b32 s14, v24, 24
	v_readlane_b32 s15, v25, 24
	v_readlane_b32 s16, v26, 24
	s_waitcnt vmcnt(39)
	v_pk_fma_f32 v[10:11], v[156:157], s[12:13], v[10:11] op_sel_hi:[0,1,1]
	v_pk_fma_f32 v[8:9], v[156:157], s[14:15], v[8:9] op_sel_hi:[0,1,1]
	v_fmac_f32_e32 v22, s16, v156
	v_readlane_b32 s12, v0, 25
	v_readlane_b32 s13, v23, 25
	v_readlane_b32 s14, v24, 25
	v_readlane_b32 s15, v25, 25
	v_readlane_b32 s16, v26, 25
	s_waitcnt vmcnt(38)
	v_pk_fma_f32 v[10:11], v[156:157], s[12:13], v[10:11] op_sel:[1,0,0] op_sel_hi:[1,1,1]
	v_pk_fma_f32 v[8:9], v[156:157], s[14:15], v[8:9] op_sel:[1,0,0] op_sel_hi:[1,1,1]
	v_fmac_f32_e32 v22, s16, v157
	v_readlane_b32 s12, v0, 26
	v_readlane_b32 s13, v23, 26
	v_readlane_b32 s14, v24, 26
	v_readlane_b32 s15, v25, 26
	v_readlane_b32 s16, v26, 26
	s_waitcnt vmcnt(37)
	v_pk_fma_f32 v[10:11], v[158:159], s[12:13], v[10:11] op_sel_hi:[0,1,1]
	v_pk_fma_f32 v[8:9], v[158:159], s[14:15], v[8:9] op_sel_hi:[0,1,1]
	v_fmac_f32_e32 v22, s16, v158
	v_readlane_b32 s12, v0, 27
	v_readlane_b32 s13, v23, 27
	v_readlane_b32 s14, v24, 27
	v_readlane_b32 s15, v25, 27
	v_readlane_b32 s16, v26, 27
	s_waitcnt vmcnt(36)
	v_pk_fma_f32 v[10:11], v[158:159], s[12:13], v[10:11] op_sel:[1,0,0] op_sel_hi:[1,1,1]
	v_pk_fma_f32 v[8:9], v[158:159], s[14:15], v[8:9] op_sel:[1,0,0] op_sel_hi:[1,1,1]
	v_fmac_f32_e32 v22, s16, v159
	v_readlane_b32 s12, v0, 28
	v_readlane_b32 s13, v23, 28
	v_readlane_b32 s14, v24, 28
	v_readlane_b32 s15, v25, 28
	v_readlane_b32 s16, v26, 28
	s_waitcnt vmcnt(35)
	v_pk_fma_f32 v[10:11], v[160:161], s[12:13], v[10:11] op_sel_hi:[0,1,1]
	v_pk_fma_f32 v[8:9], v[160:161], s[14:15], v[8:9] op_sel_hi:[0,1,1]
	v_fmac_f32_e32 v22, s16, v160
	v_readlane_b32 s12, v0, 29
	v_readlane_b32 s13, v23, 29
	v_readlane_b32 s14, v24, 29
	v_readlane_b32 s15, v25, 29
	v_readlane_b32 s16, v26, 29
	s_waitcnt vmcnt(34)
	v_pk_fma_f32 v[10:11], v[160:161], s[12:13], v[10:11] op_sel:[1,0,0] op_sel_hi:[1,1,1]
	v_pk_fma_f32 v[8:9], v[160:161], s[14:15], v[8:9] op_sel:[1,0,0] op_sel_hi:[1,1,1]
	v_fmac_f32_e32 v22, s16, v161
	v_readlane_b32 s12, v0, 30
	v_readlane_b32 s13, v23, 30
	v_readlane_b32 s14, v24, 30
	v_readlane_b32 s15, v25, 30
	v_readlane_b32 s16, v26, 30
	s_waitcnt vmcnt(33)
	v_pk_fma_f32 v[10:11], v[162:163], s[12:13], v[10:11] op_sel_hi:[0,1,1]
	v_pk_fma_f32 v[8:9], v[162:163], s[14:15], v[8:9] op_sel_hi:[0,1,1]
	v_fmac_f32_e32 v22, s16, v162
	v_readlane_b32 s12, v0, 31
	v_readlane_b32 s13, v23, 31
	v_readlane_b32 s14, v24, 31
	v_readlane_b32 s15, v25, 31
	v_readlane_b32 s16, v26, 31
	s_waitcnt vmcnt(32)
	v_pk_fma_f32 v[10:11], v[162:163], s[12:13], v[10:11] op_sel:[1,0,0] op_sel_hi:[1,1,1]
	v_pk_fma_f32 v[8:9], v[162:163], s[14:15], v[8:9] op_sel:[1,0,0] op_sel_hi:[1,1,1]
	v_fmac_f32_e32 v22, s16, v163
	v_readlane_b32 s12, v0, 32
	v_readlane_b32 s13, v23, 32
	v_readlane_b32 s14, v24, 32
	v_readlane_b32 s15, v25, 32
	v_readlane_b32 s16, v26, 32
	s_waitcnt vmcnt(31)
	v_pk_fma_f32 v[10:11], v[164:165], s[12:13], v[10:11] op_sel_hi:[0,1,1]
	v_pk_fma_f32 v[8:9], v[164:165], s[14:15], v[8:9] op_sel_hi:[0,1,1]
	v_fmac_f32_e32 v22, s16, v164
	v_readlane_b32 s12, v0, 33
	v_readlane_b32 s13, v23, 33
	v_readlane_b32 s14, v24, 33
	v_readlane_b32 s15, v25, 33
	v_readlane_b32 s16, v26, 33
	s_waitcnt vmcnt(30)
	v_pk_fma_f32 v[10:11], v[164:165], s[12:13], v[10:11] op_sel:[1,0,0] op_sel_hi:[1,1,1]
	v_pk_fma_f32 v[8:9], v[164:165], s[14:15], v[8:9] op_sel:[1,0,0] op_sel_hi:[1,1,1]
	v_fmac_f32_e32 v22, s16, v165
	v_readlane_b32 s12, v0, 34
	v_readlane_b32 s13, v23, 34
	v_readlane_b32 s14, v24, 34
	v_readlane_b32 s15, v25, 34
	v_readlane_b32 s16, v26, 34
	s_waitcnt vmcnt(29)
	v_pk_fma_f32 v[10:11], v[166:167], s[12:13], v[10:11] op_sel_hi:[0,1,1]
	v_pk_fma_f32 v[8:9], v[166:167], s[14:15], v[8:9] op_sel_hi:[0,1,1]
	v_fmac_f32_e32 v22, s16, v166
	v_readlane_b32 s12, v0, 35
	v_readlane_b32 s13, v23, 35
	v_readlane_b32 s14, v24, 35
	v_readlane_b32 s15, v25, 35
	v_readlane_b32 s16, v26, 35
	s_waitcnt vmcnt(28)
	v_pk_fma_f32 v[10:11], v[166:167], s[12:13], v[10:11] op_sel:[1,0,0] op_sel_hi:[1,1,1]
	v_pk_fma_f32 v[8:9], v[166:167], s[14:15], v[8:9] op_sel:[1,0,0] op_sel_hi:[1,1,1]
	v_fmac_f32_e32 v22, s16, v167
	v_readlane_b32 s12, v0, 36
	v_readlane_b32 s13, v23, 36
	v_readlane_b32 s14, v24, 36
	v_readlane_b32 s15, v25, 36
	v_readlane_b32 s16, v26, 36
	s_waitcnt vmcnt(27)
	v_pk_fma_f32 v[10:11], v[168:169], s[12:13], v[10:11] op_sel_hi:[0,1,1]
	v_pk_fma_f32 v[8:9], v[168:169], s[14:15], v[8:9] op_sel_hi:[0,1,1]
	v_fmac_f32_e32 v22, s16, v168
	v_readlane_b32 s12, v0, 37
	v_readlane_b32 s13, v23, 37
	v_readlane_b32 s14, v24, 37
	v_readlane_b32 s15, v25, 37
	v_readlane_b32 s16, v26, 37
	s_waitcnt vmcnt(26)
	v_pk_fma_f32 v[10:11], v[168:169], s[12:13], v[10:11] op_sel:[1,0,0] op_sel_hi:[1,1,1]
	v_pk_fma_f32 v[8:9], v[168:169], s[14:15], v[8:9] op_sel:[1,0,0] op_sel_hi:[1,1,1]
	v_fmac_f32_e32 v22, s16, v169
	v_readlane_b32 s12, v0, 38
	v_readlane_b32 s13, v23, 38
	v_readlane_b32 s14, v24, 38
	v_readlane_b32 s15, v25, 38
	v_readlane_b32 s16, v26, 38
	s_waitcnt vmcnt(25)
	v_pk_fma_f32 v[10:11], v[170:171], s[12:13], v[10:11] op_sel_hi:[0,1,1]
	v_pk_fma_f32 v[8:9], v[170:171], s[14:15], v[8:9] op_sel_hi:[0,1,1]
	v_fmac_f32_e32 v22, s16, v170
	v_readlane_b32 s12, v0, 39
	v_readlane_b32 s13, v23, 39
	v_readlane_b32 s14, v24, 39
	v_readlane_b32 s15, v25, 39
	v_readlane_b32 s16, v26, 39
	s_waitcnt vmcnt(24)
	v_pk_fma_f32 v[10:11], v[170:171], s[12:13], v[10:11] op_sel:[1,0,0] op_sel_hi:[1,1,1]
	v_pk_fma_f32 v[8:9], v[170:171], s[14:15], v[8:9] op_sel:[1,0,0] op_sel_hi:[1,1,1]
	v_fmac_f32_e32 v22, s16, v171
	v_readlane_b32 s12, v0, 40
	v_readlane_b32 s13, v23, 40
	v_readlane_b32 s14, v24, 40
	v_readlane_b32 s15, v25, 40
	v_readlane_b32 s16, v26, 40
	s_waitcnt vmcnt(23)
	v_pk_fma_f32 v[10:11], v[172:173], s[12:13], v[10:11] op_sel_hi:[0,1,1]
	v_pk_fma_f32 v[8:9], v[172:173], s[14:15], v[8:9] op_sel_hi:[0,1,1]
	v_fmac_f32_e32 v22, s16, v172
	v_readlane_b32 s12, v0, 41
	v_readlane_b32 s13, v23, 41
	v_readlane_b32 s14, v24, 41
	v_readlane_b32 s15, v25, 41
	v_readlane_b32 s16, v26, 41
	s_waitcnt vmcnt(22)
	v_pk_fma_f32 v[10:11], v[172:173], s[12:13], v[10:11] op_sel:[1,0,0] op_sel_hi:[1,1,1]
	v_pk_fma_f32 v[8:9], v[172:173], s[14:15], v[8:9] op_sel:[1,0,0] op_sel_hi:[1,1,1]
	v_fmac_f32_e32 v22, s16, v173
	v_readlane_b32 s12, v0, 42
	v_readlane_b32 s13, v23, 42
	v_readlane_b32 s14, v24, 42
	v_readlane_b32 s15, v25, 42
	v_readlane_b32 s16, v26, 42
	s_waitcnt vmcnt(21)
	v_pk_fma_f32 v[10:11], v[174:175], s[12:13], v[10:11] op_sel_hi:[0,1,1]
	v_pk_fma_f32 v[8:9], v[174:175], s[14:15], v[8:9] op_sel_hi:[0,1,1]
	v_fmac_f32_e32 v22, s16, v174
	v_readlane_b32 s12, v0, 43
	v_readlane_b32 s13, v23, 43
	v_readlane_b32 s14, v24, 43
	v_readlane_b32 s15, v25, 43
	v_readlane_b32 s16, v26, 43
	s_waitcnt vmcnt(20)
	v_pk_fma_f32 v[10:11], v[174:175], s[12:13], v[10:11] op_sel:[1,0,0] op_sel_hi:[1,1,1]
	v_pk_fma_f32 v[8:9], v[174:175], s[14:15], v[8:9] op_sel:[1,0,0] op_sel_hi:[1,1,1]
	v_fmac_f32_e32 v22, s16, v175
	v_readlane_b32 s12, v0, 44
	v_readlane_b32 s13, v23, 44
	v_readlane_b32 s14, v24, 44
	v_readlane_b32 s15, v25, 44
	v_readlane_b32 s16, v26, 44
	s_waitcnt vmcnt(19)
	v_pk_fma_f32 v[10:11], v[176:177], s[12:13], v[10:11] op_sel_hi:[0,1,1]
	v_pk_fma_f32 v[8:9], v[176:177], s[14:15], v[8:9] op_sel_hi:[0,1,1]
	v_fmac_f32_e32 v22, s16, v176
	v_readlane_b32 s12, v0, 45
	v_readlane_b32 s13, v23, 45
	v_readlane_b32 s14, v24, 45
	v_readlane_b32 s15, v25, 45
	v_readlane_b32 s16, v26, 45
	s_waitcnt vmcnt(18)
	v_pk_fma_f32 v[10:11], v[176:177], s[12:13], v[10:11] op_sel:[1,0,0] op_sel_hi:[1,1,1]
	v_pk_fma_f32 v[8:9], v[176:177], s[14:15], v[8:9] op_sel:[1,0,0] op_sel_hi:[1,1,1]
	v_fmac_f32_e32 v22, s16, v177
	v_readlane_b32 s12, v0, 46
	v_readlane_b32 s13, v23, 46
	v_readlane_b32 s14, v24, 46
	v_readlane_b32 s15, v25, 46
	v_readlane_b32 s16, v26, 46
	s_waitcnt vmcnt(17)
	v_pk_fma_f32 v[10:11], v[178:179], s[12:13], v[10:11] op_sel_hi:[0,1,1]
	v_pk_fma_f32 v[8:9], v[178:179], s[14:15], v[8:9] op_sel_hi:[0,1,1]
	v_fmac_f32_e32 v22, s16, v178
	v_readlane_b32 s12, v0, 47
	v_readlane_b32 s13, v23, 47
	v_readlane_b32 s14, v24, 47
	v_readlane_b32 s15, v25, 47
	v_readlane_b32 s16, v26, 47
	s_waitcnt vmcnt(16)
	v_pk_fma_f32 v[10:11], v[178:179], s[12:13], v[10:11] op_sel:[1,0,0] op_sel_hi:[1,1,1]
	v_pk_fma_f32 v[8:9], v[178:179], s[14:15], v[8:9] op_sel:[1,0,0] op_sel_hi:[1,1,1]
	v_fmac_f32_e32 v22, s16, v179
	v_readlane_b32 s12, v0, 48
	v_readlane_b32 s13, v23, 48
	v_readlane_b32 s14, v24, 48
	v_readlane_b32 s15, v25, 48
	v_readlane_b32 s16, v26, 48
	s_waitcnt vmcnt(15)
	v_pk_fma_f32 v[10:11], v[180:181], s[12:13], v[10:11] op_sel_hi:[0,1,1]
	v_pk_fma_f32 v[8:9], v[180:181], s[14:15], v[8:9] op_sel_hi:[0,1,1]
	v_fmac_f32_e32 v22, s16, v180
	v_readlane_b32 s12, v0, 49
	v_readlane_b32 s13, v23, 49
	v_readlane_b32 s14, v24, 49
	v_readlane_b32 s15, v25, 49
	v_readlane_b32 s16, v26, 49
	s_waitcnt vmcnt(14)
	v_pk_fma_f32 v[10:11], v[180:181], s[12:13], v[10:11] op_sel:[1,0,0] op_sel_hi:[1,1,1]
	v_pk_fma_f32 v[8:9], v[180:181], s[14:15], v[8:9] op_sel:[1,0,0] op_sel_hi:[1,1,1]
	v_fmac_f32_e32 v22, s16, v181
	v_readlane_b32 s12, v0, 50
	v_readlane_b32 s13, v23, 50
	v_readlane_b32 s14, v24, 50
	v_readlane_b32 s15, v25, 50
	v_readlane_b32 s16, v26, 50
	s_waitcnt vmcnt(13)
	v_pk_fma_f32 v[10:11], v[182:183], s[12:13], v[10:11] op_sel_hi:[0,1,1]
	v_pk_fma_f32 v[8:9], v[182:183], s[14:15], v[8:9] op_sel_hi:[0,1,1]
	v_fmac_f32_e32 v22, s16, v182
	v_readlane_b32 s12, v0, 51
	v_readlane_b32 s13, v23, 51
	v_readlane_b32 s14, v24, 51
	v_readlane_b32 s15, v25, 51
	v_readlane_b32 s16, v26, 51
	s_waitcnt vmcnt(12)
	v_pk_fma_f32 v[10:11], v[182:183], s[12:13], v[10:11] op_sel:[1,0,0] op_sel_hi:[1,1,1]
	v_pk_fma_f32 v[8:9], v[182:183], s[14:15], v[8:9] op_sel:[1,0,0] op_sel_hi:[1,1,1]
	v_fmac_f32_e32 v22, s16, v183
	v_readlane_b32 s12, v0, 52
	v_readlane_b32 s13, v23, 52
	v_readlane_b32 s14, v24, 52
	v_readlane_b32 s15, v25, 52
	v_readlane_b32 s16, v26, 52
	s_waitcnt vmcnt(11)
	v_pk_fma_f32 v[10:11], v[184:185], s[12:13], v[10:11] op_sel_hi:[0,1,1]
	v_pk_fma_f32 v[8:9], v[184:185], s[14:15], v[8:9] op_sel_hi:[0,1,1]
	v_fmac_f32_e32 v22, s16, v184
	v_readlane_b32 s12, v0, 53
	v_readlane_b32 s13, v23, 53
	v_readlane_b32 s14, v24, 53
	v_readlane_b32 s15, v25, 53
	v_readlane_b32 s16, v26, 53
	s_waitcnt vmcnt(10)
	v_pk_fma_f32 v[10:11], v[184:185], s[12:13], v[10:11] op_sel:[1,0,0] op_sel_hi:[1,1,1]
	v_pk_fma_f32 v[8:9], v[184:185], s[14:15], v[8:9] op_sel:[1,0,0] op_sel_hi:[1,1,1]
	v_fmac_f32_e32 v22, s16, v185
	v_readlane_b32 s12, v0, 54
	v_readlane_b32 s13, v23, 54
	v_readlane_b32 s14, v24, 54
	v_readlane_b32 s15, v25, 54
	v_readlane_b32 s16, v26, 54
	s_waitcnt vmcnt(9)
	v_pk_fma_f32 v[10:11], v[186:187], s[12:13], v[10:11] op_sel_hi:[0,1,1]
	v_pk_fma_f32 v[8:9], v[186:187], s[14:15], v[8:9] op_sel_hi:[0,1,1]
	v_fmac_f32_e32 v22, s16, v186
	v_readlane_b32 s12, v0, 55
	v_readlane_b32 s13, v23, 55
	v_readlane_b32 s14, v24, 55
	v_readlane_b32 s15, v25, 55
	v_readlane_b32 s16, v26, 55
	s_waitcnt vmcnt(8)
	v_pk_fma_f32 v[10:11], v[186:187], s[12:13], v[10:11] op_sel:[1,0,0] op_sel_hi:[1,1,1]
	v_pk_fma_f32 v[8:9], v[186:187], s[14:15], v[8:9] op_sel:[1,0,0] op_sel_hi:[1,1,1]
	v_fmac_f32_e32 v22, s16, v187
	v_readlane_b32 s12, v0, 56
	v_readlane_b32 s13, v23, 56
	v_readlane_b32 s14, v24, 56
	v_readlane_b32 s15, v25, 56
	v_readlane_b32 s16, v26, 56
	s_waitcnt vmcnt(7)
	v_pk_fma_f32 v[10:11], v[188:189], s[12:13], v[10:11] op_sel_hi:[0,1,1]
	v_pk_fma_f32 v[8:9], v[188:189], s[14:15], v[8:9] op_sel_hi:[0,1,1]
	v_fmac_f32_e32 v22, s16, v188
	v_readlane_b32 s12, v0, 57
	v_readlane_b32 s13, v23, 57
	v_readlane_b32 s14, v24, 57
	v_readlane_b32 s15, v25, 57
	v_readlane_b32 s16, v26, 57
	s_waitcnt vmcnt(6)
	v_pk_fma_f32 v[10:11], v[188:189], s[12:13], v[10:11] op_sel:[1,0,0] op_sel_hi:[1,1,1]
	v_pk_fma_f32 v[8:9], v[188:189], s[14:15], v[8:9] op_sel:[1,0,0] op_sel_hi:[1,1,1]
	v_fmac_f32_e32 v22, s16, v189
	v_readlane_b32 s12, v0, 58
	v_readlane_b32 s13, v23, 58
	v_readlane_b32 s14, v24, 58
	v_readlane_b32 s15, v25, 58
	v_readlane_b32 s16, v26, 58
	s_waitcnt vmcnt(5)
	v_pk_fma_f32 v[10:11], v[190:191], s[12:13], v[10:11] op_sel_hi:[0,1,1]
	v_pk_fma_f32 v[8:9], v[190:191], s[14:15], v[8:9] op_sel_hi:[0,1,1]
	v_fmac_f32_e32 v22, s16, v190
	v_readlane_b32 s12, v0, 59
	v_readlane_b32 s13, v23, 59
	v_readlane_b32 s14, v24, 59
	v_readlane_b32 s15, v25, 59
	v_readlane_b32 s16, v26, 59
	s_waitcnt vmcnt(4)
	v_pk_fma_f32 v[10:11], v[190:191], s[12:13], v[10:11] op_sel:[1,0,0] op_sel_hi:[1,1,1]
	v_pk_fma_f32 v[8:9], v[190:191], s[14:15], v[8:9] op_sel:[1,0,0] op_sel_hi:[1,1,1]
	v_fmac_f32_e32 v22, s16, v191
	v_readlane_b32 s12, v0, 60
	v_readlane_b32 s13, v23, 60
	v_readlane_b32 s14, v24, 60
	v_readlane_b32 s15, v25, 60
	v_readlane_b32 s16, v26, 60
	s_waitcnt vmcnt(3)
	v_pk_fma_f32 v[10:11], v[192:193], s[12:13], v[10:11] op_sel_hi:[0,1,1]
	v_pk_fma_f32 v[8:9], v[192:193], s[14:15], v[8:9] op_sel_hi:[0,1,1]
	v_fmac_f32_e32 v22, s16, v192
	v_readlane_b32 s12, v0, 61
	v_readlane_b32 s13, v23, 61
	v_readlane_b32 s14, v24, 61
	v_readlane_b32 s15, v25, 61
	v_readlane_b32 s16, v26, 61
	s_waitcnt vmcnt(2)
	v_pk_fma_f32 v[10:11], v[192:193], s[12:13], v[10:11] op_sel:[1,0,0] op_sel_hi:[1,1,1]
	v_pk_fma_f32 v[8:9], v[192:193], s[14:15], v[8:9] op_sel:[1,0,0] op_sel_hi:[1,1,1]
	v_fmac_f32_e32 v22, s16, v193
	v_readlane_b32 s12, v0, 62
	v_readlane_b32 s13, v23, 62
	v_readlane_b32 s14, v24, 62
	v_readlane_b32 s15, v25, 62
	v_readlane_b32 s16, v26, 62
	s_waitcnt vmcnt(1)
	v_pk_fma_f32 v[10:11], v[194:195], s[12:13], v[10:11] op_sel_hi:[0,1,1]
	v_pk_fma_f32 v[8:9], v[194:195], s[14:15], v[8:9] op_sel_hi:[0,1,1]
	v_fmac_f32_e32 v22, s16, v194
	v_readlane_b32 s12, v0, 63
	v_readlane_b32 s13, v23, 63
	v_readlane_b32 s14, v24, 63
	v_readlane_b32 s15, v25, 63
	v_readlane_b32 s16, v26, 63
	s_waitcnt vmcnt(0)
	v_pk_fma_f32 v[10:11], v[194:195], s[12:13], v[10:11] op_sel:[1,0,0] op_sel_hi:[1,1,1]
	v_pk_fma_f32 v[8:9], v[194:195], s[14:15], v[8:9] op_sel:[1,0,0] op_sel_hi:[1,1,1]
	v_fmac_f32_e32 v22, s16, v195
	s_movk_i32 s12, 0x6000
	s_mov_b32 s13, 0x9000
	s_mov_b32 s14, 0xc000
	s_mov_b32 s15, 0xf000
	s_mov_b32 s16, 0x12000
	s_mov_b32 s70, 64
	s_mov_b64 s[8:9], 0
	s_and_b64 vcc, exec, s[6:7]
	s_cbranch_vccz .LBB0_20
	v_lshlrev_b32_e32 v0, 3, v17
	v_and_b32_e32 v6, 0xffffffc0, v0
	v_ashrrev_i32_e32 v7, 31, v6
	v_lshl_add_u64 v[6:7], v[6:7], 2, v[2:3]
	v_add_co_u32_e32 v12, vcc, 0x3000, v6
	global_store_dword v[6:7], v10, off
	s_nop 0
	v_addc_co_u32_e32 v13, vcc, 0, v7, vcc
	v_add_co_u32_e32 v10, vcc, 0x6000, v6
	global_store_dword v[12:13], v11, off
	s_nop 0
	v_addc_co_u32_e32 v11, vcc, 0, v7, vcc
	global_store_dword v[10:11], v8, off
	v_add_co_u32_e32 v10, vcc, 0x9000, v6
	v_add_u32_e32 v17, s33, v17
	s_nop 0
	v_addc_co_u32_e32 v11, vcc, 0, v7, vcc
	v_add_co_u32_e32 v6, vcc, 0xc000, v6
	v_add_u32_e32 v19, s3, v19
	s_nop 0
	v_addc_co_u32_e32 v7, vcc, 0, v7, vcc
	v_cmp_lt_i32_e32 vcc, s69, v17
	s_or_b64 s[4:5], vcc, s[4:5]
	global_store_dword v[10:11], v9, off
	global_store_dword v[6:7], v22, off
	s_andn2_b64 exec, exec, s[4:5]
	s_cbranch_execnz .LBB0_19
